# v26 variant: recurrence sk and read-out dot chains interleaved, operand reads issued earlier in the step
# baseline (speedup 1.0000x reference)
.LBB0_1238:
	s_or_b64 exec, exec, s[18:19]
	s_waitcnt lgkmcnt(0)
	s_barrier
	s_cmp_lg_u32 s100, 0
	s_cselect_b32 s97, 0x800, 0
	v_add_u32_e32 v167, s97, v114
	ds_read_b128 v[72:75], v114 offset:41216
	ds_read_b128 v[68:71], v114 offset:45312
	ds_read_b128 v[64:67], v114 offset:49408
	ds_read_b128 v[56:59], v114 offset:53504
	ds_read_b128 v[60:63], v167 offset:28928
	ds_read2st64_b32 v[214:215], v115 offset1:1
	s_waitcnt lgkmcnt(0)
	v_dot2_f32_f16 v151, v127, v72, 0
	v_dot2_f32_f16 v151, v126, v73, v151
	v_dot2_f32_f16 v151, v125, v74, v151
	v_dot2_f32_f16 v151, v124, v75, v151
	ds_read_b128 v[134:137], v114 offset:41344
	ds_read_b128 v[138:141], v114 offset:45440
	ds_read_b128 v[142:145], v114 offset:49536
	v_add_f32_dpp v151, v151, v151 quad_perm:[1,0,3,2] row_mask:0xf bank_mask:0xf bound_ctrl:1
	ds_read_b128 v[130:133], v167 offset:29056
	ds_read_b128 v[146:149], v114 offset:53632
	v_add_f32_dpp v151, v151, v151 quad_perm:[2,3,0,1] row_mask:0xf bank_mask:0xf bound_ctrl:1
	s_nop 1
	v_add_f32_dpp v151, v151, v151 row_half_mirror row_mask:0xf bank_mask:0xf bound_ctrl:1
	v_cvt_pkrtz_f16_f32 v152, -v151, -v151
	v_pk_mul_f16 v153, v152, v68
	v_pk_mul_f16 v154, v152, v69
	v_pk_mul_f16 v155, v152, v70
	v_pk_mul_f16 v156, v152, v71
	v_pk_fma_f16 v153, v214, v64, v153
	v_pk_fma_f16 v154, v214, v65, v154
	v_pk_fma_f16 v155, v214, v66, v155
	v_pk_fma_f16 v156, v214, v67, v156
	v_pk_fma_f16 v127, v127, v60, v153
	v_pk_fma_f16 v126, v126, v61, v154
	v_pk_fma_f16 v125, v125, v62, v155
	v_pk_fma_f16 v124, v124, v63, v156
	s_waitcnt lgkmcnt(0)
	v_dot2_f32_f16 v151, v127, v134, 0
	v_dot2_f32_f16 v157, v127, v56, 0
	v_dot2_f32_f16 v151, v126, v135, v151
	v_dot2_f32_f16 v157, v126, v57, v157
	v_dot2_f32_f16 v151, v125, v136, v151
	v_dot2_f32_f16 v157, v125, v58, v157
	v_dot2_f32_f16 v151, v124, v137, v151
	v_dot2_f32_f16 v157, v124, v59, v157
	ds_read_b128 v[72:75], v114 offset:41472
	ds_read_b128 v[68:71], v114 offset:45568
	v_add_f32_dpp v151, v151, v151 quad_perm:[1,0,3,2] row_mask:0xf bank_mask:0xf bound_ctrl:1
	ds_read_b128 v[64:67], v114 offset:49664
	ds_read_b128 v[60:63], v167 offset:29184
	v_add_f32_dpp v151, v151, v151 quad_perm:[2,3,0,1] row_mask:0xf bank_mask:0xf bound_ctrl:1
	ds_read_b128 v[56:59], v114 offset:53760
	ds_read2st64_b32 v[216:217], v115 offset0:2 offset1:3
	v_add_f32_dpp v151, v151, v151 row_half_mirror row_mask:0xf bank_mask:0xf bound_ctrl:1
	v_cvt_pkrtz_f16_f32 v152, -v151, -v151
	v_pk_mul_f16 v153, v152, v138
	v_pk_mul_f16 v154, v152, v139
	v_pk_mul_f16 v155, v152, v140
	v_pk_mul_f16 v156, v152, v141
	v_pk_fma_f16 v153, v215, v142, v153
	v_pk_fma_f16 v154, v215, v143, v154
	v_pk_fma_f16 v155, v215, v144, v155
	v_pk_fma_f16 v156, v215, v145, v156
	v_pk_fma_f16 v127, v127, v130, v153
	v_pk_fma_f16 v126, v126, v131, v154
	v_pk_fma_f16 v125, v125, v132, v155
	v_pk_fma_f16 v124, v124, v133, v156
	s_waitcnt lgkmcnt(0)
	v_dot2_f32_f16 v151, v127, v72, 0
	v_dot2_f32_f16 v158, v127, v146, 0
	v_dot2_f32_f16 v151, v126, v73, v151
	v_dot2_f32_f16 v158, v126, v147, v158
	v_dot2_f32_f16 v151, v125, v74, v151
	v_dot2_f32_f16 v158, v125, v148, v158
	v_dot2_f32_f16 v151, v124, v75, v151
	v_dot2_f32_f16 v158, v124, v149, v158
	ds_read_b128 v[134:137], v114 offset:41600
	ds_read_b128 v[138:141], v114 offset:45696
	v_add_f32_dpp v151, v151, v151 quad_perm:[1,0,3,2] row_mask:0xf bank_mask:0xf bound_ctrl:1
	ds_read_b128 v[142:145], v114 offset:49792
	ds_read_b128 v[130:133], v167 offset:29312
	v_add_f32_dpp v151, v151, v151 quad_perm:[2,3,0,1] row_mask:0xf bank_mask:0xf bound_ctrl:1
	ds_read_b128 v[146:149], v114 offset:53888
	ds_write2st64_b32 v116, v157, v158 offset0:0 offset1:8
	v_add_f32_dpp v151, v151, v151 row_half_mirror row_mask:0xf bank_mask:0xf bound_ctrl:1
	v_cvt_pkrtz_f16_f32 v152, -v151, -v151
	v_pk_mul_f16 v153, v152, v68
	v_pk_mul_f16 v154, v152, v69
	v_pk_mul_f16 v155, v152, v70
	v_pk_mul_f16 v156, v152, v71
	v_pk_fma_f16 v153, v216, v64, v153
	v_pk_fma_f16 v154, v216, v65, v154
	v_pk_fma_f16 v155, v216, v66, v155
	v_pk_fma_f16 v156, v216, v67, v156
	v_pk_fma_f16 v127, v127, v60, v153
	v_pk_fma_f16 v126, v126, v61, v154
	v_pk_fma_f16 v125, v125, v62, v155
	v_pk_fma_f16 v124, v124, v63, v156
	s_waitcnt lgkmcnt(0)
	v_dot2_f32_f16 v151, v127, v134, 0
	v_dot2_f32_f16 v157, v127, v56, 0
	v_dot2_f32_f16 v151, v126, v135, v151
	v_dot2_f32_f16 v157, v126, v57, v157
	v_dot2_f32_f16 v151, v125, v136, v151
	v_dot2_f32_f16 v157, v125, v58, v157
	v_dot2_f32_f16 v151, v124, v137, v151
	v_dot2_f32_f16 v157, v124, v59, v157
	ds_read_b128 v[72:75], v114 offset:41728
	ds_read_b128 v[68:71], v114 offset:45824
	v_add_f32_dpp v151, v151, v151 quad_perm:[1,0,3,2] row_mask:0xf bank_mask:0xf bound_ctrl:1
	ds_read_b128 v[64:67], v114 offset:49920
	ds_read_b128 v[60:63], v167 offset:29440
	v_add_f32_dpp v151, v151, v151 quad_perm:[2,3,0,1] row_mask:0xf bank_mask:0xf bound_ctrl:1
	ds_read_b128 v[56:59], v114 offset:54016
	ds_read2st64_b32 v[214:215], v115 offset0:4 offset1:5
	v_add_f32_dpp v151, v151, v151 row_half_mirror row_mask:0xf bank_mask:0xf bound_ctrl:1
	v_cvt_pkrtz_f16_f32 v152, -v151, -v151
	v_pk_mul_f16 v153, v152, v138
	v_pk_mul_f16 v154, v152, v139
	v_pk_mul_f16 v155, v152, v140
	v_pk_mul_f16 v156, v152, v141
	v_pk_fma_f16 v153, v217, v142, v153
	v_pk_fma_f16 v154, v217, v143, v154
	v_pk_fma_f16 v155, v217, v144, v155
	v_pk_fma_f16 v156, v217, v145, v156
	v_pk_fma_f16 v127, v127, v130, v153
	v_pk_fma_f16 v126, v126, v131, v154
	v_pk_fma_f16 v125, v125, v132, v155
	v_pk_fma_f16 v124, v124, v133, v156
	s_waitcnt lgkmcnt(0)
	v_dot2_f32_f16 v151, v127, v72, 0
	v_dot2_f32_f16 v158, v127, v146, 0
	v_dot2_f32_f16 v151, v126, v73, v151
	v_dot2_f32_f16 v158, v126, v147, v158
	v_dot2_f32_f16 v151, v125, v74, v151
	v_dot2_f32_f16 v158, v125, v148, v158
	v_dot2_f32_f16 v151, v124, v75, v151
	v_dot2_f32_f16 v158, v124, v149, v158
	ds_read_b128 v[134:137], v114 offset:41856
	ds_read_b128 v[138:141], v114 offset:45952
	v_add_f32_dpp v151, v151, v151 quad_perm:[1,0,3,2] row_mask:0xf bank_mask:0xf bound_ctrl:1
	ds_read_b128 v[142:145], v114 offset:50048
	ds_read_b128 v[130:133], v167 offset:29568
	v_add_f32_dpp v151, v151, v151 quad_perm:[2,3,0,1] row_mask:0xf bank_mask:0xf bound_ctrl:1
	ds_read_b128 v[146:149], v114 offset:54144
	ds_write2st64_b32 v116, v157, v158 offset0:16 offset1:24
	v_add_f32_dpp v151, v151, v151 row_half_mirror row_mask:0xf bank_mask:0xf bound_ctrl:1
	v_cvt_pkrtz_f16_f32 v152, -v151, -v151
	v_pk_mul_f16 v153, v152, v68
	v_pk_mul_f16 v154, v152, v69
	v_pk_mul_f16 v155, v152, v70
	v_pk_mul_f16 v156, v152, v71
	v_pk_fma_f16 v153, v214, v64, v153
	v_pk_fma_f16 v154, v214, v65, v154
	v_pk_fma_f16 v155, v214, v66, v155
	v_pk_fma_f16 v156, v214, v67, v156
	v_pk_fma_f16 v127, v127, v60, v153
	v_pk_fma_f16 v126, v126, v61, v154
	v_pk_fma_f16 v125, v125, v62, v155
	v_pk_fma_f16 v124, v124, v63, v156
	s_waitcnt lgkmcnt(0)
	v_dot2_f32_f16 v151, v127, v134, 0
	v_dot2_f32_f16 v157, v127, v56, 0
	v_dot2_f32_f16 v151, v126, v135, v151
	v_dot2_f32_f16 v157, v126, v57, v157
	v_dot2_f32_f16 v151, v125, v136, v151
	v_dot2_f32_f16 v157, v125, v58, v157
	v_dot2_f32_f16 v151, v124, v137, v151
	v_dot2_f32_f16 v157, v124, v59, v157
	ds_read_b128 v[72:75], v114 offset:41984
	ds_read_b128 v[68:71], v114 offset:46080
	v_add_f32_dpp v151, v151, v151 quad_perm:[1,0,3,2] row_mask:0xf bank_mask:0xf bound_ctrl:1
	ds_read_b128 v[64:67], v114 offset:50176
	ds_read_b128 v[60:63], v167 offset:29696
	v_add_f32_dpp v151, v151, v151 quad_perm:[2,3,0,1] row_mask:0xf bank_mask:0xf bound_ctrl:1
	ds_read_b128 v[56:59], v114 offset:54272
	ds_read2st64_b32 v[216:217], v115 offset0:6 offset1:7
	v_add_f32_dpp v151, v151, v151 row_half_mirror row_mask:0xf bank_mask:0xf bound_ctrl:1
	v_cvt_pkrtz_f16_f32 v152, -v151, -v151
	v_pk_mul_f16 v153, v152, v138
	v_pk_mul_f16 v154, v152, v139
	v_pk_mul_f16 v155, v152, v140
	v_pk_mul_f16 v156, v152, v141
	v_pk_fma_f16 v153, v215, v142, v153
	v_pk_fma_f16 v154, v215, v143, v154
	v_pk_fma_f16 v155, v215, v144, v155
	v_pk_fma_f16 v156, v215, v145, v156
	v_pk_fma_f16 v127, v127, v130, v153
	v_pk_fma_f16 v126, v126, v131, v154
	v_pk_fma_f16 v125, v125, v132, v155
	v_pk_fma_f16 v124, v124, v133, v156
	s_waitcnt lgkmcnt(0)
	v_dot2_f32_f16 v151, v127, v72, 0
	v_dot2_f32_f16 v158, v127, v146, 0
	v_dot2_f32_f16 v151, v126, v73, v151
	v_dot2_f32_f16 v158, v126, v147, v158
	v_dot2_f32_f16 v151, v125, v74, v151
	v_dot2_f32_f16 v158, v125, v148, v158
	v_dot2_f32_f16 v151, v124, v75, v151
	v_dot2_f32_f16 v158, v124, v149, v158
	ds_read_b128 v[134:137], v114 offset:42112
	ds_read_b128 v[138:141], v114 offset:46208
	v_add_f32_dpp v151, v151, v151 quad_perm:[1,0,3,2] row_mask:0xf bank_mask:0xf bound_ctrl:1
	ds_read_b128 v[142:145], v114 offset:50304
	ds_read_b128 v[130:133], v167 offset:29824
	v_add_f32_dpp v151, v151, v151 quad_perm:[2,3,0,1] row_mask:0xf bank_mask:0xf bound_ctrl:1
	ds_read_b128 v[146:149], v114 offset:54400
	ds_write2st64_b32 v116, v157, v158 offset0:32 offset1:40
	v_add_f32_dpp v151, v151, v151 row_half_mirror row_mask:0xf bank_mask:0xf bound_ctrl:1
	v_cvt_pkrtz_f16_f32 v152, -v151, -v151
	v_pk_mul_f16 v153, v152, v68
	v_pk_mul_f16 v154, v152, v69
	v_pk_mul_f16 v155, v152, v70
	v_pk_mul_f16 v156, v152, v71
	v_pk_fma_f16 v153, v216, v64, v153
	v_pk_fma_f16 v154, v216, v65, v154
	v_pk_fma_f16 v155, v216, v66, v155
	v_pk_fma_f16 v156, v216, v67, v156
	v_pk_fma_f16 v127, v127, v60, v153
	v_pk_fma_f16 v126, v126, v61, v154
	v_pk_fma_f16 v125, v125, v62, v155
	v_pk_fma_f16 v124, v124, v63, v156
	s_waitcnt lgkmcnt(0)
	v_dot2_f32_f16 v151, v127, v134, 0
	v_dot2_f32_f16 v157, v127, v56, 0
	v_dot2_f32_f16 v151, v126, v135, v151
	v_dot2_f32_f16 v157, v126, v57, v157
	v_dot2_f32_f16 v151, v125, v136, v151
	v_dot2_f32_f16 v157, v125, v58, v157
	v_dot2_f32_f16 v151, v124, v137, v151
	v_dot2_f32_f16 v157, v124, v59, v157
	ds_read_b128 v[72:75], v114 offset:42240
	ds_read_b128 v[68:71], v114 offset:46336
	v_add_f32_dpp v151, v151, v151 quad_perm:[1,0,3,2] row_mask:0xf bank_mask:0xf bound_ctrl:1
	ds_read_b128 v[64:67], v114 offset:50432
	ds_read_b128 v[60:63], v167 offset:29952
	v_add_f32_dpp v151, v151, v151 quad_perm:[2,3,0,1] row_mask:0xf bank_mask:0xf bound_ctrl:1
	ds_read_b128 v[56:59], v114 offset:54528
	ds_read2st64_b32 v[214:215], v115 offset0:8 offset1:9
	v_add_f32_dpp v151, v151, v151 row_half_mirror row_mask:0xf bank_mask:0xf bound_ctrl:1
	v_cvt_pkrtz_f16_f32 v152, -v151, -v151
	v_pk_mul_f16 v153, v152, v138
	v_pk_mul_f16 v154, v152, v139
	v_pk_mul_f16 v155, v152, v140
	v_pk_mul_f16 v156, v152, v141
	v_pk_fma_f16 v153, v217, v142, v153
	v_pk_fma_f16 v154, v217, v143, v154
	v_pk_fma_f16 v155, v217, v144, v155
	v_pk_fma_f16 v156, v217, v145, v156
	v_pk_fma_f16 v127, v127, v130, v153
	v_pk_fma_f16 v126, v126, v131, v154
	v_pk_fma_f16 v125, v125, v132, v155
	v_pk_fma_f16 v124, v124, v133, v156
	s_waitcnt lgkmcnt(0)
	v_dot2_f32_f16 v151, v127, v72, 0
	v_dot2_f32_f16 v158, v127, v146, 0
	v_dot2_f32_f16 v151, v126, v73, v151
	v_dot2_f32_f16 v158, v126, v147, v158
	v_dot2_f32_f16 v151, v125, v74, v151
	v_dot2_f32_f16 v158, v125, v148, v158
	v_dot2_f32_f16 v151, v124, v75, v151
	v_dot2_f32_f16 v158, v124, v149, v158
	ds_read_b128 v[134:137], v114 offset:42368
	ds_read_b128 v[138:141], v114 offset:46464
	v_add_f32_dpp v151, v151, v151 quad_perm:[1,0,3,2] row_mask:0xf bank_mask:0xf bound_ctrl:1
	ds_read_b128 v[142:145], v114 offset:50560
	ds_read_b128 v[130:133], v167 offset:30080
	v_add_f32_dpp v151, v151, v151 quad_perm:[2,3,0,1] row_mask:0xf bank_mask:0xf bound_ctrl:1
	ds_read_b128 v[146:149], v114 offset:54656
	ds_write2st64_b32 v116, v157, v158 offset0:48 offset1:56
	v_add_f32_dpp v151, v151, v151 row_half_mirror row_mask:0xf bank_mask:0xf bound_ctrl:1
	v_cvt_pkrtz_f16_f32 v152, -v151, -v151
	v_pk_mul_f16 v153, v152, v68
	v_pk_mul_f16 v154, v152, v69
	v_pk_mul_f16 v155, v152, v70
	v_pk_mul_f16 v156, v152, v71
	v_pk_fma_f16 v153, v214, v64, v153
	v_pk_fma_f16 v154, v214, v65, v154
	v_pk_fma_f16 v155, v214, v66, v155
	v_pk_fma_f16 v156, v214, v67, v156
	v_pk_fma_f16 v127, v127, v60, v153
	v_pk_fma_f16 v126, v126, v61, v154
	v_pk_fma_f16 v125, v125, v62, v155
	v_pk_fma_f16 v124, v124, v63, v156
	s_waitcnt lgkmcnt(0)
	v_dot2_f32_f16 v151, v127, v134, 0
	v_dot2_f32_f16 v157, v127, v56, 0
	v_dot2_f32_f16 v151, v126, v135, v151
	v_dot2_f32_f16 v157, v126, v57, v157
	v_dot2_f32_f16 v151, v125, v136, v151
	v_dot2_f32_f16 v157, v125, v58, v157
	v_dot2_f32_f16 v151, v124, v137, v151
	v_dot2_f32_f16 v157, v124, v59, v157
	ds_read_b128 v[72:75], v114 offset:42496
	ds_read_b128 v[68:71], v114 offset:46592
	v_add_f32_dpp v151, v151, v151 quad_perm:[1,0,3,2] row_mask:0xf bank_mask:0xf bound_ctrl:1
	ds_read_b128 v[64:67], v114 offset:50688
	ds_read_b128 v[60:63], v167 offset:30208
	v_add_f32_dpp v151, v151, v151 quad_perm:[2,3,0,1] row_mask:0xf bank_mask:0xf bound_ctrl:1
	ds_read_b128 v[56:59], v114 offset:54784
	ds_read2st64_b32 v[216:217], v115 offset0:10 offset1:11
	v_add_f32_dpp v151, v151, v151 row_half_mirror row_mask:0xf bank_mask:0xf bound_ctrl:1
	v_cvt_pkrtz_f16_f32 v152, -v151, -v151
	v_pk_mul_f16 v153, v152, v138
	v_pk_mul_f16 v154, v152, v139
	v_pk_mul_f16 v155, v152, v140
	v_pk_mul_f16 v156, v152, v141
	v_pk_fma_f16 v153, v215, v142, v153
	v_pk_fma_f16 v154, v215, v143, v154
	v_pk_fma_f16 v155, v215, v144, v155
	v_pk_fma_f16 v156, v215, v145, v156
	v_pk_fma_f16 v127, v127, v130, v153
	v_pk_fma_f16 v126, v126, v131, v154
	v_pk_fma_f16 v125, v125, v132, v155
	v_pk_fma_f16 v124, v124, v133, v156
	s_waitcnt lgkmcnt(0)
	v_dot2_f32_f16 v151, v127, v72, 0
	v_dot2_f32_f16 v158, v127, v146, 0
	v_dot2_f32_f16 v151, v126, v73, v151
	v_dot2_f32_f16 v158, v126, v147, v158
	v_dot2_f32_f16 v151, v125, v74, v151
	v_dot2_f32_f16 v158, v125, v148, v158
	v_dot2_f32_f16 v151, v124, v75, v151
	v_dot2_f32_f16 v158, v124, v149, v158
	ds_read_b128 v[134:137], v114 offset:42624
	ds_read_b128 v[138:141], v114 offset:46720
	v_add_f32_dpp v151, v151, v151 quad_perm:[1,0,3,2] row_mask:0xf bank_mask:0xf bound_ctrl:1
	ds_read_b128 v[142:145], v114 offset:50816
	ds_read_b128 v[130:133], v167 offset:30336
	v_add_f32_dpp v151, v151, v151 quad_perm:[2,3,0,1] row_mask:0xf bank_mask:0xf bound_ctrl:1
	ds_read_b128 v[146:149], v114 offset:54912
	ds_write2st64_b32 v116, v157, v158 offset0:64 offset1:72
	v_add_f32_dpp v151, v151, v151 row_half_mirror row_mask:0xf bank_mask:0xf bound_ctrl:1
	v_cvt_pkrtz_f16_f32 v152, -v151, -v151
	v_pk_mul_f16 v153, v152, v68
	v_pk_mul_f16 v154, v152, v69
	v_pk_mul_f16 v155, v152, v70
	v_pk_mul_f16 v156, v152, v71
	v_pk_fma_f16 v153, v216, v64, v153
	v_pk_fma_f16 v154, v216, v65, v154
	v_pk_fma_f16 v155, v216, v66, v155
	v_pk_fma_f16 v156, v216, v67, v156
	v_pk_fma_f16 v127, v127, v60, v153
	v_pk_fma_f16 v126, v126, v61, v154
	v_pk_fma_f16 v125, v125, v62, v155
	v_pk_fma_f16 v124, v124, v63, v156
	s_waitcnt lgkmcnt(0)
	v_dot2_f32_f16 v151, v127, v134, 0
	v_dot2_f32_f16 v157, v127, v56, 0
	v_dot2_f32_f16 v151, v126, v135, v151
	v_dot2_f32_f16 v157, v126, v57, v157
	v_dot2_f32_f16 v151, v125, v136, v151
	v_dot2_f32_f16 v157, v125, v58, v157
	v_dot2_f32_f16 v151, v124, v137, v151
	v_dot2_f32_f16 v157, v124, v59, v157
	ds_read_b128 v[72:75], v114 offset:42752
	ds_read_b128 v[68:71], v114 offset:46848
	v_add_f32_dpp v151, v151, v151 quad_perm:[1,0,3,2] row_mask:0xf bank_mask:0xf bound_ctrl:1
	ds_read_b128 v[64:67], v114 offset:50944
	ds_read_b128 v[60:63], v167 offset:30464
	v_add_f32_dpp v151, v151, v151 quad_perm:[2,3,0,1] row_mask:0xf bank_mask:0xf bound_ctrl:1
	ds_read_b128 v[56:59], v114 offset:55040
	ds_read2st64_b32 v[214:215], v115 offset0:12 offset1:13
	v_add_f32_dpp v151, v151, v151 row_half_mirror row_mask:0xf bank_mask:0xf bound_ctrl:1
	v_cvt_pkrtz_f16_f32 v152, -v151, -v151
	v_pk_mul_f16 v153, v152, v138
	v_pk_mul_f16 v154, v152, v139
	v_pk_mul_f16 v155, v152, v140
	v_pk_mul_f16 v156, v152, v141
	v_pk_fma_f16 v153, v217, v142, v153
	v_pk_fma_f16 v154, v217, v143, v154
	v_pk_fma_f16 v155, v217, v144, v155
	v_pk_fma_f16 v156, v217, v145, v156
	v_pk_fma_f16 v127, v127, v130, v153
	v_pk_fma_f16 v126, v126, v131, v154
	v_pk_fma_f16 v125, v125, v132, v155
	v_pk_fma_f16 v124, v124, v133, v156
	s_waitcnt lgkmcnt(0)
	v_dot2_f32_f16 v151, v127, v72, 0
	v_dot2_f32_f16 v158, v127, v146, 0
	v_dot2_f32_f16 v151, v126, v73, v151
	v_dot2_f32_f16 v158, v126, v147, v158
	v_dot2_f32_f16 v151, v125, v74, v151
	v_dot2_f32_f16 v158, v125, v148, v158
	v_dot2_f32_f16 v151, v124, v75, v151
	v_dot2_f32_f16 v158, v124, v149, v158
	ds_read_b128 v[134:137], v114 offset:42880
	ds_read_b128 v[138:141], v114 offset:46976
	v_add_f32_dpp v151, v151, v151 quad_perm:[1,0,3,2] row_mask:0xf bank_mask:0xf bound_ctrl:1
	ds_read_b128 v[142:145], v114 offset:51072
	ds_read_b128 v[130:133], v167 offset:30592
	v_add_f32_dpp v151, v151, v151 quad_perm:[2,3,0,1] row_mask:0xf bank_mask:0xf bound_ctrl:1
	ds_read_b128 v[146:149], v114 offset:55168
	ds_write2st64_b32 v116, v157, v158 offset0:80 offset1:88
	v_add_f32_dpp v151, v151, v151 row_half_mirror row_mask:0xf bank_mask:0xf bound_ctrl:1
	v_cvt_pkrtz_f16_f32 v152, -v151, -v151
	v_pk_mul_f16 v153, v152, v68
	v_pk_mul_f16 v154, v152, v69
	v_pk_mul_f16 v155, v152, v70
	v_pk_mul_f16 v156, v152, v71
	v_pk_fma_f16 v153, v214, v64, v153
	v_pk_fma_f16 v154, v214, v65, v154
	v_pk_fma_f16 v155, v214, v66, v155
	v_pk_fma_f16 v156, v214, v67, v156
	v_pk_fma_f16 v127, v127, v60, v153
	v_pk_fma_f16 v126, v126, v61, v154
	v_pk_fma_f16 v125, v125, v62, v155
	v_pk_fma_f16 v124, v124, v63, v156
	s_waitcnt lgkmcnt(0)
	v_dot2_f32_f16 v151, v127, v134, 0
	v_dot2_f32_f16 v157, v127, v56, 0
	v_dot2_f32_f16 v151, v126, v135, v151
	v_dot2_f32_f16 v157, v126, v57, v157
	v_dot2_f32_f16 v151, v125, v136, v151
	v_dot2_f32_f16 v157, v125, v58, v157
	v_dot2_f32_f16 v151, v124, v137, v151
	v_dot2_f32_f16 v157, v124, v59, v157
	ds_read_b128 v[72:75], v114 offset:43008
	ds_read_b128 v[68:71], v114 offset:47104
	v_add_f32_dpp v151, v151, v151 quad_perm:[1,0,3,2] row_mask:0xf bank_mask:0xf bound_ctrl:1
	ds_read_b128 v[64:67], v114 offset:51200
	ds_read_b128 v[60:63], v167 offset:30720
	v_add_f32_dpp v151, v151, v151 quad_perm:[2,3,0,1] row_mask:0xf bank_mask:0xf bound_ctrl:1
	ds_read_b128 v[56:59], v114 offset:55296
	ds_read2st64_b32 v[216:217], v115 offset0:14 offset1:15
	v_add_f32_dpp v151, v151, v151 row_half_mirror row_mask:0xf bank_mask:0xf bound_ctrl:1
	v_cvt_pkrtz_f16_f32 v152, -v151, -v151
	v_pk_mul_f16 v153, v152, v138
	v_pk_mul_f16 v154, v152, v139
	v_pk_mul_f16 v155, v152, v140
	v_pk_mul_f16 v156, v152, v141
	v_pk_fma_f16 v153, v215, v142, v153
	v_pk_fma_f16 v154, v215, v143, v154
	v_pk_fma_f16 v155, v215, v144, v155
	v_pk_fma_f16 v156, v215, v145, v156
	v_pk_fma_f16 v127, v127, v130, v153
	v_pk_fma_f16 v126, v126, v131, v154
	v_pk_fma_f16 v125, v125, v132, v155
	v_pk_fma_f16 v124, v124, v133, v156
	s_waitcnt lgkmcnt(0)
	v_dot2_f32_f16 v151, v127, v72, 0
	v_dot2_f32_f16 v158, v127, v146, 0
	v_dot2_f32_f16 v151, v126, v73, v151
	v_dot2_f32_f16 v158, v126, v147, v158
	v_dot2_f32_f16 v151, v125, v74, v151
	v_dot2_f32_f16 v158, v125, v148, v158
	v_dot2_f32_f16 v151, v124, v75, v151
	v_dot2_f32_f16 v158, v124, v149, v158
	ds_read_b128 v[134:137], v114 offset:43136
	ds_read_b128 v[138:141], v114 offset:47232
	v_add_f32_dpp v151, v151, v151 quad_perm:[1,0,3,2] row_mask:0xf bank_mask:0xf bound_ctrl:1
	ds_read_b128 v[142:145], v114 offset:51328
	ds_read_b128 v[130:133], v167 offset:30848
	v_add_f32_dpp v151, v151, v151 quad_perm:[2,3,0,1] row_mask:0xf bank_mask:0xf bound_ctrl:1
	ds_read_b128 v[146:149], v114 offset:55424
	ds_write2st64_b32 v116, v157, v158 offset0:96 offset1:104
	v_add_f32_dpp v151, v151, v151 row_half_mirror row_mask:0xf bank_mask:0xf bound_ctrl:1
	v_cvt_pkrtz_f16_f32 v152, -v151, -v151
	v_pk_mul_f16 v153, v152, v68
	v_pk_mul_f16 v154, v152, v69
	v_pk_mul_f16 v155, v152, v70
	v_pk_mul_f16 v156, v152, v71
	v_pk_fma_f16 v153, v216, v64, v153
	v_pk_fma_f16 v154, v216, v65, v154
	v_pk_fma_f16 v155, v216, v66, v155
	v_pk_fma_f16 v156, v216, v67, v156
	v_pk_fma_f16 v127, v127, v60, v153
	v_pk_fma_f16 v126, v126, v61, v154
	v_pk_fma_f16 v125, v125, v62, v155
	v_pk_fma_f16 v124, v124, v63, v156
	s_waitcnt lgkmcnt(0)
	v_dot2_f32_f16 v151, v127, v134, 0
	v_dot2_f32_f16 v157, v127, v56, 0
	v_dot2_f32_f16 v151, v126, v135, v151
	v_dot2_f32_f16 v157, v126, v57, v157
	v_dot2_f32_f16 v151, v125, v136, v151
	v_dot2_f32_f16 v157, v125, v58, v157
	v_dot2_f32_f16 v151, v124, v137, v151
	v_dot2_f32_f16 v157, v124, v59, v157
	s_nop 1
	v_add_f32_dpp v151, v151, v151 quad_perm:[1,0,3,2] row_mask:0xf bank_mask:0xf bound_ctrl:1
	s_nop 1
	v_add_f32_dpp v151, v151, v151 quad_perm:[2,3,0,1] row_mask:0xf bank_mask:0xf bound_ctrl:1
	s_nop 1
	v_add_f32_dpp v151, v151, v151 row_half_mirror row_mask:0xf bank_mask:0xf bound_ctrl:1
	v_cvt_pkrtz_f16_f32 v152, -v151, -v151
	v_pk_mul_f16 v153, v152, v138
	v_pk_mul_f16 v154, v152, v139
	v_pk_mul_f16 v155, v152, v140
	v_pk_mul_f16 v156, v152, v141
	v_pk_fma_f16 v153, v217, v142, v153
	v_pk_fma_f16 v154, v217, v143, v154
	v_pk_fma_f16 v155, v217, v144, v155
	v_pk_fma_f16 v156, v217, v145, v156
	v_pk_fma_f16 v127, v127, v130, v153
	v_pk_fma_f16 v126, v126, v131, v154
	v_pk_fma_f16 v125, v125, v132, v155
	v_pk_fma_f16 v124, v124, v133, v156
	v_dot2_f32_f16 v158, v127, v146, 0
	v_dot2_f32_f16 v158, v126, v147, v158
	v_dot2_f32_f16 v158, v125, v148, v158
	v_dot2_f32_f16 v158, v124, v149, v158
	s_nop 2
	ds_write2st64_b32 v116, v157, v158 offset0:112 offset1:120
	s_xor_b32 s100, s100, 0xe100
	s_cmpk_lg_i32 s30, 0x80
	s_cbranch_scc0 .LBB0_1250
	s_mov_b32 s4, s30
	s_and_saveexec_b64 s[18:19], s[10:11]
	s_cbranch_execnz .LBB0_1229
	s_branch .LBB0_1230
